# final LayerNorm: gamma/beta loaded once before the row loop (32 dependent loads + 14 waits per iteration removed); plus previous edits
# speedup vs baseline: 1.0024x; 1.0024x over previous
; template <class T> __device__ __forceinline__ T* lnd(T* p) { asm volatile("" : "+s"(p)); return p; }
; __device__ __forceinline__ int lnd_tid() { int t = threadIdx.x; asm volatile("" : "+v"(t)); return t; }
; #define GAS __attribute__((address_space(1)))
; __device__ void ln_final_phase(const h16* z0, const float* g0, const float* b0, float* out0) {
;     const GAS h16* z = (const GAS h16*)lnd(z0); const float* g = lnd(g0); const float* b = lnd(b0); float* out = lnd(out0);
;     const int tidl = lnd_tid(), lane = tidl & 63, gw = blockIdx.x * 8 + (tidl >> 6), nw = gridDim.x * 8;
;     for (int row0 = gw; row0 < NT; row0 += 2 * nw) {
;         f16x8 hv[2][4];
; #pragma unroll
;         for (int r = 0; r < 2; ++r)
; #pragma unroll
;             for (int i = 0; i < 4; ++i) hv[r][i] = *(const GAS f16x8*)(z + (size_t)(row0 + r * nw) * DM + 8 * (lane + 64 * i));
; #pragma unroll
;         for (int r = 0; r < 2; ++r) {
;             const int row = row0 + r * nw; float s = 0.f;
; #pragma unroll
;             for (int i = 0; i < 4; ++i)
; #pragma unroll
;                 for (int j = 0; j < 8; ++j) s += (float)hv[r][i][j];
; #pragma unroll
;             for (int o = 32; o >= 1; o >>= 1) s += __shfl_xor(s, o);
;             const float mean = s * (1.0f / DM); float q = 0.f;
; #pragma unroll
;             for (int i = 0; i < 4; ++i)
; #pragma unroll
;                 for (int j = 0; j < 8; ++j) { const float d = (float)hv[r][i][j] - mean; q += d * d; }
; #pragma unroll
;             for (int o = 32; o >= 1; o >>= 1) q += __shfl_xor(q, o);
;             const float rstd = rsqrtf(q * (1.0f / DM) + LN_EPS);
; #pragma unroll
;             for (int i = 0; i < 4; ++i) { const int col = 8 * (lane + 64 * i);
;                 const f32x4 g0v = ldg4(g + col), g1v = ldg4(g + col + 4), b0v = ldg4(b + col), b1v = ldg4(b + col + 4);
.LBB0_805:
	v_readlane_b32 s4, v253, 0
	s_add_u32 s0, s68, 0xcac4000
	v_readlane_b32 s14, v253, 10
	v_readlane_b32 s15, v253, 11
	v_readlane_b32 s18, v253, 14
	v_readlane_b32 s19, v253, 15
	s_addc_u32 s1, s69, 0
	s_mov_b64 s[14:15], s[18:19]
	s_add_u32 s2, s14, 0x6000
	s_addc_u32 s3, s15, 0
	v_readlane_b32 s5, v253, 1
	s_add_u32 s4, s48, 0x6000
	v_readlane_b32 s6, v253, 2
	s_addc_u32 s5, s49, 0
	v_readlane_b32 s6, v253, 27
	v_ashrrev_i32_e32 v0, 6, v252
	v_readlane_b32 s7, v253, 3
	v_add_u32_e32 v36, s6, v0
	s_movk_i32 s6, 0x4000
	v_cmp_gt_i32_e32 vcc, s6, v36
	v_readlane_b32 s8, v253, 4
	v_readlane_b32 s9, v253, 5
	v_readlane_b32 s10, v253, 6
	v_readlane_b32 s11, v253, 7
	v_readlane_b32 s12, v253, 8
	v_readlane_b32 s13, v253, 9
	v_readlane_b32 s16, v253, 12
	v_readlane_b32 s17, v253, 13
	s_and_saveexec_b64 s[6:7], vcc
	s_cbranch_execz .LBB0_808
	v_and_b32_e32 v1, 64, v221
	v_add_u32_e32 v1, 64, v1
	v_xor_b32_e32 v3, 32, v221
	v_cmp_lt_i32_e32 vcc, v3, v1
	v_lshlrev_b32_e32 v0, 3, v252
	v_and_b32_e32 v0, 0x1f8, v0
	v_cndmask_b32_e32 v3, v221, v3, vcc
	v_lshlrev_b32_e32 v33, 2, v3
	v_xor_b32_e32 v3, 16, v221
	v_cmp_lt_i32_e32 vcc, v3, v1
	v_mov_b32_e32 v13, 0
	v_or_b32_e32 v2, 0x400, v0
	v_cndmask_b32_e32 v3, v221, v3, vcc
	v_lshlrev_b32_e32 v84, 2, v3
	v_xor_b32_e32 v3, 8, v221
	v_cmp_lt_i32_e32 vcc, v3, v1
	v_lshlrev_b32_e32 v12, 2, v0
	v_or_b32_e32 v4, 0x600, v0
	v_cndmask_b32_e32 v3, v221, v3, vcc
	v_lshlrev_b32_e32 v85, 2, v3
	v_xor_b32_e32 v3, 4, v221
	v_cmp_lt_i32_e32 vcc, v3, v1
	v_lshl_add_u64 v[14:15], s[2:3], 0, v[12:13]
	v_lshl_add_u64 v[16:17], s[4:5], 0, v[12:13]
	v_cndmask_b32_e32 v3, v221, v3, vcc
	v_lshlrev_b32_e32 v86, 2, v3
	v_xor_b32_e32 v3, 2, v221
	v_cmp_lt_i32_e32 vcc, v3, v1
	v_lshlrev_b32_e32 v12, 2, v2
	v_lshl_add_u64 v[18:19], s[2:3], 0, v[12:13]
	v_cndmask_b32_e32 v3, v221, v3, vcc
	v_lshlrev_b32_e32 v87, 2, v3
	v_xor_b32_e32 v3, 1, v221
	v_cmp_lt_i32_e32 vcc, v3, v1
	v_lshl_add_u64 v[20:21], s[4:5], 0, v[12:13]
	v_lshlrev_b32_e32 v12, 2, v4
	v_cndmask_b32_e32 v1, v221, v3, vcc
	v_lshl_add_u64 v[22:23], s[2:3], 0, v[12:13]
	v_lshl_add_u64 v[24:25], s[4:5], 0, v[12:13]
	v_lshlrev_b32_e32 v12, 1, v0
	s_lshl_b32 s6, s70, 3
	v_lshlrev_b32_e32 v88, 2, v1
	v_lshl_add_u64 v[26:27], s[0:1], 0, v[12:13]
	s_mov_b64 s[0:1], 0
	v_lshlrev_b32_e32 v12, 2, v0
	v_lshlrev_b32_e32 v28, 2, v2
	v_mov_b32_e32 v29, v13
	s_mov_b32 s2, 0x3a000000
	v_lshlrev_b32_e32 v30, 2, v4
	v_mov_b32_e32 v31, v13
	v_mov_b32_e32 v32, 0x3727c5ac
	s_mov_b32 s3, 0x800000
	s_movk_i32 s4, 0x3fff
	global_load_dwordx4 v[150:153], v[14:15], off
	global_load_dwordx4 v[154:157], v[14:15], off offset:16
	global_load_dwordx4 v[158:161], v[14:15], off offset:2048
	global_load_dwordx4 v[162:165], v[14:15], off offset:2064
	global_load_dwordx4 v[166:169], v[18:19], off
	global_load_dwordx4 v[170:173], v[18:19], off offset:16
	global_load_dwordx4 v[174:177], v[22:23], off
	global_load_dwordx4 v[178:181], v[22:23], off offset:16
	global_load_dwordx4 v[182:185], v[16:17], off
	global_load_dwordx4 v[186:189], v[16:17], off offset:16
	global_load_dwordx4 v[190:193], v[16:17], off offset:2048
	global_load_dwordx4 v[194:197], v[16:17], off offset:2064
	global_load_dwordx4 v[198:201], v[20:21], off
	global_load_dwordx4 v[202:205], v[20:21], off offset:16
	global_load_dwordx4 v[206:209], v[24:25], off
	global_load_dwordx4 v[210:213], v[24:25], off offset:16
.LBB0_807:
	v_ashrrev_i32_e32 v37, 31, v36
	v_lshlrev_b64 v[0:1], 12, v[36:37]
	v_lshl_add_u64 v[0:1], v[26:27], 0, v[0:1]
	v_add_u32_e32 v34, s6, v36
	global_load_dwordx4 v[44:47], v[0:1], off
	global_load_dwordx4 v[52:55], v[0:1], off offset:1024
	global_load_dwordx4 v[60:63], v[0:1], off offset:2048
	global_load_dwordx4 v[66:69], v[0:1], off offset:3072
	v_ashrrev_i32_e32 v35, 31, v34
	v_lshlrev_b64 v[0:1], 12, v[34:35]
	v_lshl_add_u64 v[38:39], v[26:27], 0, v[0:1]
	global_load_dwordx4 v[70:73], v[38:39], off
	global_load_dwordx4 v[74:77], v[38:39], off offset:1024
	global_load_dwordx4 v[78:81], v[38:39], off offset:2048
	global_load_dwordx4 v[8:11], v[38:39], off offset:3072
	v_lshlrev_b64 v[36:37], 13, v[36:37]
	v_lshl_add_u64 v[36:37], s[50:51], 0, v[36:37]
	s_waitcnt vmcnt(0)
	v_mov_b32_e32 v0, v154
	v_mov_b32_e32 v1, v155
	v_mov_b32_e32 v2, v156
	v_mov_b32_e32 v3, v157
	v_mov_b32_e32 v4, v150
	v_mov_b32_e32 v5, v151
	v_mov_b32_e32 v6, v152
	v_mov_b32_e32 v7, v153
	v_mov_b32_e32 v90, v186
	v_mov_b32_e32 v91, v187
	v_mov_b32_e32 v92, v188
	v_mov_b32_e32 v93, v189
	v_mov_b32_e32 v94, v182
	v_mov_b32_e32 v95, v183
	v_mov_b32_e32 v96, v184
	v_mov_b32_e32 v97, v185
	v_cvt_f32_f16_e32 v42, v44
	v_cvt_f32_f16_sdwa v43, v44 dst_sel:DWORD dst_unused:UNUSED_PAD src0_sel:WORD_1
	v_cvt_f32_f16_e32 v44, v45
	v_cvt_f32_f16_sdwa v45, v45 dst_sel:DWORD dst_unused:UNUSED_PAD src0_sel:WORD_1
	v_cvt_f32_f16_e32 v38, v46
	v_cvt_f32_f16_e32 v122, v10
	v_cvt_f32_f16_sdwa v123, v10 dst_sel:DWORD dst_unused:UNUSED_PAD src0_sel:WORD_1
	v_cvt_f32_f16_e32 v82, v11
	v_cvt_f32_f16_sdwa v83, v11 dst_sel:DWORD dst_unused:UNUSED_PAD src0_sel:WORD_1
	v_cvt_f32_f16_e32 v10, v8
	v_cvt_f32_f16_sdwa v11, v8 dst_sel:DWORD dst_unused:UNUSED_PAD src0_sel:WORD_1
	v_add_f32_e32 v8, 0, v42
	v_cvt_f32_f16_sdwa v39, v46 dst_sel:DWORD dst_unused:UNUSED_PAD src0_sel:WORD_1
	v_add_f32_e32 v8, v8, v43
	v_cvt_f32_f16_e32 v40, v47
	v_add_f32_e32 v8, v8, v44
	v_cvt_f32_f16_sdwa v41, v47 dst_sel:DWORD dst_unused:UNUSED_PAD src0_sel:WORD_1
	v_add_f32_e32 v8, v8, v45
	v_cvt_f32_f16_e32 v50, v52
	v_add_f32_e32 v8, v8, v38
	v_cvt_f32_f16_sdwa v51, v52 dst_sel:DWORD dst_unused:UNUSED_PAD src0_sel:WORD_1
	v_add_f32_e32 v8, v8, v39
	v_cvt_f32_f16_e32 v52, v53
; __device__ void ln_final_phase(const h16* z0, const float* g0, const float* b0, float* out0) {
;     ...
;         for (int r = 0; r < 2; ++r) {
;             const int row = row0 + r * nw; float s = 0.f;
; #pragma unroll
;             for (int i = 0; i < 4; ++i)
; #pragma unroll
;                 for (int j = 0; j < 8; ++j) s += (float)hv[r][i][j];
; #pragma unroll
;             for (int o = 32; o >= 1; o >>= 1) s += __shfl_xor(s, o);
;             const float mean = s * (1.0f / DM); float q = 0.f;
	v_add_f32_e32 v8, v8, v40
	v_cvt_f32_f16_sdwa v53, v53 dst_sel:DWORD dst_unused:UNUSED_PAD src0_sel:WORD_1
	v_add_f32_e32 v8, v8, v41
	v_cvt_f32_f16_e32 v46, v54
	v_add_f32_e32 v8, v8, v50
	v_cvt_f32_f16_sdwa v47, v54 dst_sel:DWORD dst_unused:UNUSED_PAD src0_sel:WORD_1
	v_add_f32_e32 v8, v8, v51
	v_cvt_f32_f16_e32 v48, v55
	v_add_f32_e32 v8, v8, v52
	v_cvt_f32_f16_sdwa v49, v55 dst_sel:DWORD dst_unused:UNUSED_PAD src0_sel:WORD_1
	v_add_f32_e32 v8, v8, v53
	v_cvt_f32_f16_e32 v58, v60
	v_add_f32_e32 v8, v8, v46
	v_cvt_f32_f16_sdwa v59, v60 dst_sel:DWORD dst_unused:UNUSED_PAD src0_sel:WORD_1
	v_add_f32_e32 v8, v8, v47
	v_cvt_f32_f16_e32 v60, v61
	v_add_f32_e32 v8, v8, v48
	v_cvt_f32_f16_sdwa v61, v61 dst_sel:DWORD dst_unused:UNUSED_PAD src0_sel:WORD_1
	v_add_f32_e32 v8, v8, v49
	v_cvt_f32_f16_e32 v54, v62
	v_add_f32_e32 v8, v8, v58
	v_cvt_f32_f16_sdwa v55, v62 dst_sel:DWORD dst_unused:UNUSED_PAD src0_sel:WORD_1
	v_add_f32_e32 v8, v8, v59
	v_cvt_f32_f16_e32 v56, v63
	v_add_f32_e32 v8, v8, v60
	v_cvt_f32_f16_sdwa v57, v63 dst_sel:DWORD dst_unused:UNUSED_PAD src0_sel:WORD_1
	v_add_f32_e32 v8, v8, v61
	v_cvt_f32_f16_e32 v62, v68
	v_cvt_f32_f16_sdwa v63, v68 dst_sel:DWORD dst_unused:UNUSED_PAD src0_sel:WORD_1
	v_cvt_f32_f16_e32 v68, v66
	v_add_f32_e32 v8, v8, v54
	v_cvt_f32_f16_e32 v64, v69
	v_cvt_f32_f16_sdwa v65, v69 dst_sel:DWORD dst_unused:UNUSED_PAD src0_sel:WORD_1
	v_cvt_f32_f16_sdwa v69, v66 dst_sel:DWORD dst_unused:UNUSED_PAD src0_sel:WORD_1
	v_add_f32_e32 v8, v8, v55
	v_cvt_f32_f16_e32 v66, v67
	v_cvt_f32_f16_e32 v102, v70
	v_add_f32_e32 v8, v8, v56
	v_cvt_f32_f16_sdwa v67, v67 dst_sel:DWORD dst_unused:UNUSED_PAD src0_sel:WORD_1
	v_cvt_f32_f16_sdwa v103, v70 dst_sel:DWORD dst_unused:UNUSED_PAD src0_sel:WORD_1
	v_add_f32_e32 v8, v8, v57
	v_cvt_f32_f16_e32 v104, v71
	v_add_f32_e32 v8, v8, v68
	v_cvt_f32_f16_sdwa v105, v71 dst_sel:DWORD dst_unused:UNUSED_PAD src0_sel:WORD_1
	v_add_f32_e32 v8, v8, v69
	v_cvt_f32_f16_e32 v98, v72
	v_add_f32_e32 v70, 0, v102
	v_add_f32_e32 v8, v8, v66
	v_cvt_f32_f16_sdwa v99, v72 dst_sel:DWORD dst_unused:UNUSED_PAD src0_sel:WORD_1
	v_add_f32_e32 v70, v70, v103
	v_add_f32_e32 v8, v8, v67
	v_cvt_f32_f16_e32 v100, v73
	v_add_f32_e32 v70, v70, v104
	v_add_f32_e32 v8, v8, v62
	v_cvt_f32_f16_sdwa v101, v73 dst_sel:DWORD dst_unused:UNUSED_PAD src0_sel:WORD_1
	v_add_f32_e32 v70, v70, v105
	v_add_f32_e32 v8, v8, v63
	v_cvt_f32_f16_e32 v110, v74
	v_add_f32_e32 v70, v70, v98
	v_add_f32_e32 v8, v8, v64
	v_cvt_f32_f16_sdwa v111, v74 dst_sel:DWORD dst_unused:UNUSED_PAD src0_sel:WORD_1
	v_add_f32_e32 v70, v70, v99
	v_add_f32_e32 v8, v8, v65
	v_cvt_f32_f16_e32 v112, v75
	v_add_f32_e32 v70, v70, v100
	ds_bpermute_b32 v71, v33, v8
	v_cvt_f32_f16_sdwa v113, v75 dst_sel:DWORD dst_unused:UNUSED_PAD src0_sel:WORD_1
	v_add_f32_e32 v70, v70, v101
	v_cvt_f32_f16_e32 v106, v76
	v_add_f32_e32 v70, v70, v110
	v_cvt_f32_f16_sdwa v107, v76 dst_sel:DWORD dst_unused:UNUSED_PAD src0_sel:WORD_1
	v_add_f32_e32 v70, v70, v111
	v_cvt_f32_f16_e32 v108, v77
	v_add_f32_e32 v70, v70, v112
	v_cvt_f32_f16_sdwa v109, v77 dst_sel:DWORD dst_unused:UNUSED_PAD src0_sel:WORD_1
	v_add_f32_e32 v70, v70, v113
	s_waitcnt lgkmcnt(0)
	v_add_f32_e32 v8, v8, v71
	v_cvt_f32_f16_e32 v118, v78
	ds_bpermute_b32 v71, v84, v8
	v_add_f32_e32 v70, v70, v106
	v_cvt_f32_f16_sdwa v119, v78 dst_sel:DWORD dst_unused:UNUSED_PAD src0_sel:WORD_1
	v_add_f32_e32 v70, v70, v107
	v_cvt_f32_f16_e32 v120, v79
	v_add_f32_e32 v70, v70, v108
	v_cvt_f32_f16_sdwa v121, v79 dst_sel:DWORD dst_unused:UNUSED_PAD src0_sel:WORD_1
	v_add_f32_e32 v70, v70, v109
	v_cvt_f32_f16_e32 v114, v80
	v_add_f32_e32 v70, v70, v118
	v_cvt_f32_f16_sdwa v115, v80 dst_sel:DWORD dst_unused:UNUSED_PAD src0_sel:WORD_1
	s_waitcnt lgkmcnt(0)
	v_add_f32_e32 v8, v8, v71
	v_add_f32_e32 v70, v70, v119
	v_cvt_f32_f16_e32 v116, v81
	ds_bpermute_b32 v71, v85, v8
	v_add_f32_e32 v70, v70, v120
	v_cvt_f32_f16_sdwa v117, v81 dst_sel:DWORD dst_unused:UNUSED_PAD src0_sel:WORD_1
	v_add_f32_e32 v70, v70, v121
	v_add_f32_e32 v70, v70, v114
	v_add_f32_e32 v70, v70, v115
	v_add_f32_e32 v70, v70, v116
	v_cvt_f32_f16_e32 v124, v9
	s_waitcnt lgkmcnt(0)
	v_add_f32_e32 v8, v8, v71
	v_add_f32_e32 v70, v70, v117
	v_cvt_f32_f16_sdwa v125, v9 dst_sel:DWORD dst_unused:UNUSED_PAD src0_sel:WORD_1
	ds_bpermute_b32 v71, v86, v8
	v_add_f32_e32 v9, v70, v10
	v_add_f32_e32 v9, v9, v11
	v_add_f32_e32 v9, v9, v124
	v_add_f32_e32 v9, v9, v125
	v_add_f32_e32 v9, v9, v122
	s_waitcnt lgkmcnt(0)
	v_add_f32_e32 v8, v8, v71
	v_add_f32_e32 v9, v9, v123
	ds_bpermute_b32 v71, v87, v8
	v_add_f32_e32 v9, v9, v82
	v_add_f32_e32 v9, v9, v83
	ds_bpermute_b32 v70, v33, v9
	s_waitcnt lgkmcnt(1)
	v_add_f32_e32 v8, v8, v71
	ds_bpermute_b32 v71, v88, v8
	s_waitcnt lgkmcnt(1)
	v_add_f32_e32 v9, v9, v70
	ds_bpermute_b32 v70, v84, v9
	s_waitcnt lgkmcnt(1)
	v_add_f32_e32 v8, v8, v71
	v_mul_f32_e32 v8, 0x3a000000, v8
	v_pk_add_f32 v[126:127], v[42:43], v[8:9] op_sel_hi:[1,0] neg_lo:[0,1] neg_hi:[0,1]
	v_pk_add_f32 v[128:129], v[44:45], v[8:9] op_sel_hi:[1,0] neg_lo:[0,1] neg_hi:[0,1]
	s_waitcnt lgkmcnt(0)
	v_add_f32_e32 v9, v9, v70
	ds_bpermute_b32 v42, v85, v9
	v_pk_add_f32 v[130:131], v[38:39], v[8:9] op_sel_hi:[1,0] neg_lo:[0,1] neg_hi:[0,1]
	v_pk_add_f32 v[132:133], v[40:41], v[8:9] op_sel_hi:[1,0] neg_lo:[0,1] neg_hi:[0,1]
	v_pk_add_f32 v[134:135], v[50:51], v[8:9] op_sel_hi:[1,0] neg_lo:[0,1] neg_hi:[0,1]
	v_pk_add_f32 v[136:137], v[52:53], v[8:9] op_sel_hi:[1,0] neg_lo:[0,1] neg_hi:[0,1]
	s_waitcnt lgkmcnt(0)
; __device__ void ln_final_phase(const h16* z0, const float* g0, const float* b0, float* out0) {
;     ...
;             const float mean = s * (1.0f / DM); float q = 0.f;
; #pragma unroll
;             for (int i = 0; i < 4; ++i)
; #pragma unroll
;                 for (int j = 0; j < 8; ++j) { const float d = (float)hv[r][i][j] - mean; q += d * d; }
; #pragma unroll
;             for (int o = 32; o >= 1; o >>= 1) q += __shfl_xor(q, o);
	v_add_f32_e32 v9, v9, v42
	ds_bpermute_b32 v38, v86, v9
	v_pk_add_f32 v[138:139], v[46:47], v[8:9] op_sel_hi:[1,0] neg_lo:[0,1] neg_hi:[0,1]
	v_pk_add_f32 v[140:141], v[48:49], v[8:9] op_sel_hi:[1,0] neg_lo:[0,1] neg_hi:[0,1]
	v_pk_add_f32 v[78:79], v[58:59], v[8:9] op_sel_hi:[1,0] neg_lo:[0,1] neg_hi:[0,1]
	v_pk_add_f32 v[80:81], v[60:61], v[8:9] op_sel_hi:[1,0] neg_lo:[0,1] neg_hi:[0,1]
	s_waitcnt lgkmcnt(0)
	v_add_f32_e32 v9, v9, v38
	ds_bpermute_b32 v38, v87, v9
	v_pk_add_f32 v[74:75], v[54:55], v[8:9] op_sel_hi:[1,0] neg_lo:[0,1] neg_hi:[0,1]
	v_pk_add_f32 v[76:77], v[56:57], v[8:9] op_sel_hi:[1,0] neg_lo:[0,1] neg_hi:[0,1]
	v_pk_add_f32 v[70:71], v[68:69], v[8:9] op_sel_hi:[1,0] neg_lo:[0,1] neg_hi:[0,1]
	v_pk_add_f32 v[72:73], v[66:67], v[8:9] op_sel_hi:[1,0] neg_lo:[0,1] neg_hi:[0,1]
	s_waitcnt lgkmcnt(0)
	v_add_f32_e32 v9, v9, v38
	ds_bpermute_b32 v38, v88, v9
	v_pk_add_f32 v[66:67], v[62:63], v[8:9] op_sel_hi:[1,0] neg_lo:[0,1] neg_hi:[0,1]
	v_pk_add_f32 v[68:69], v[64:65], v[8:9] op_sel_hi:[1,0] neg_lo:[0,1] neg_hi:[0,1]
	v_mov_b32_e32 v39, v127
	v_pk_mul_f32 v[142:143], v[66:67], v[66:67]
	s_waitcnt lgkmcnt(0)
	v_add_f32_e32 v8, v9, v38
	v_mul_f32_e32 v46, 0x3a000000, v8
	v_pk_add_f32 v[52:53], v[102:103], v[46:47] op_sel_hi:[1,0] neg_lo:[0,1] neg_hi:[0,1]
	v_pk_add_f32 v[56:57], v[104:105], v[46:47] op_sel_hi:[1,0] neg_lo:[0,1] neg_hi:[0,1]
	v_mov_b32_e32 v38, v53
	v_mov_b32_e32 v8, v52
	v_mov_b32_e32 v9, v126
	v_pk_mul_f32 v[38:39], v[38:39], v[38:39]
	v_pk_add_f32 v[42:43], v[98:99], v[46:47] op_sel_hi:[1,0] neg_lo:[0,1] neg_hi:[0,1]
	v_pk_fma_f32 v[8:9], v[8:9], v[8:9], v[38:39]
	v_mov_b32_e32 v38, v56
	v_mov_b32_e32 v39, v128
	v_pk_fma_f32 v[8:9], v[38:39], v[38:39], v[8:9]
	v_mov_b32_e32 v38, v57
	v_mov_b32_e32 v39, v129
	v_pk_fma_f32 v[8:9], v[38:39], v[38:39], v[8:9]
	v_mov_b32_e32 v38, v42
	v_mov_b32_e32 v39, v130
	v_pk_add_f32 v[48:49], v[100:101], v[46:47] op_sel_hi:[1,0] neg_lo:[0,1] neg_hi:[0,1]
	v_pk_fma_f32 v[8:9], v[38:39], v[38:39], v[8:9]
	v_mov_b32_e32 v38, v43
	v_mov_b32_e32 v39, v131
	v_pk_fma_f32 v[8:9], v[38:39], v[38:39], v[8:9]
	v_mov_b32_e32 v38, v48
	v_mov_b32_e32 v39, v132
	v_pk_fma_f32 v[8:9], v[38:39], v[38:39], v[8:9]
	v_mov_b32_e32 v38, v49
	v_mov_b32_e32 v39, v133
	v_pk_add_f32 v[54:55], v[110:111], v[46:47] op_sel_hi:[1,0] neg_lo:[0,1] neg_hi:[0,1]
	v_pk_fma_f32 v[8:9], v[38:39], v[38:39], v[8:9]
	v_mov_b32_e32 v38, v54
	v_mov_b32_e32 v39, v134
	v_pk_add_f32 v[58:59], v[112:113], v[46:47] op_sel_hi:[1,0] neg_lo:[0,1] neg_hi:[0,1]
	v_pk_fma_f32 v[8:9], v[38:39], v[38:39], v[8:9]
	v_mov_b32_e32 v38, v55
	v_mov_b32_e32 v39, v135
	v_pk_fma_f32 v[8:9], v[38:39], v[38:39], v[8:9]
	v_mov_b32_e32 v38, v58
	v_mov_b32_e32 v39, v136
	v_pk_add_f32 v[44:45], v[106:107], v[46:47] op_sel_hi:[1,0] neg_lo:[0,1] neg_hi:[0,1]
	v_pk_fma_f32 v[8:9], v[38:39], v[38:39], v[8:9]
	v_mov_b32_e32 v38, v59
	v_mov_b32_e32 v39, v137
	v_pk_fma_f32 v[8:9], v[38:39], v[38:39], v[8:9]
	v_mov_b32_e32 v38, v44
	v_mov_b32_e32 v39, v138
	v_pk_add_f32 v[50:51], v[108:109], v[46:47] op_sel_hi:[1,0] neg_lo:[0,1] neg_hi:[0,1]
	v_pk_fma_f32 v[8:9], v[38:39], v[38:39], v[8:9]
	v_mov_b32_e32 v38, v45
	v_mov_b32_e32 v39, v139
	v_pk_fma_f32 v[8:9], v[38:39], v[38:39], v[8:9]
	v_mov_b32_e32 v38, v50
	v_mov_b32_e32 v39, v140
	v_pk_add_f32 v[40:41], v[118:119], v[46:47] op_sel_hi:[1,0] neg_lo:[0,1] neg_hi:[0,1]
	v_pk_fma_f32 v[8:9], v[38:39], v[38:39], v[8:9]
	v_mov_b32_e32 v38, v51
	v_mov_b32_e32 v39, v141
	v_pk_fma_f32 v[8:9], v[38:39], v[38:39], v[8:9]
	v_mov_b32_e32 v38, v40
	v_mov_b32_e32 v39, v78
	v_pk_fma_f32 v[8:9], v[38:39], v[38:39], v[8:9]
	v_mov_b32_e32 v38, v41
	v_mov_b32_e32 v39, v79
	v_pk_add_f32 v[64:65], v[120:121], v[46:47] op_sel_hi:[1,0] neg_lo:[0,1] neg_hi:[0,1]
	v_pk_fma_f32 v[98:99], v[38:39], v[38:39], v[8:9]
	v_mov_b32_e32 v100, v64
	v_mov_b32_e32 v101, v80
	v_pk_add_f32 v[60:61], v[114:115], v[46:47] op_sel_hi:[1,0] neg_lo:[0,1] neg_hi:[0,1]
	v_pk_fma_f32 v[98:99], v[100:101], v[100:101], v[98:99]
	v_mov_b32_e32 v100, v65
	v_mov_b32_e32 v101, v81
	v_pk_fma_f32 v[98:99], v[100:101], v[100:101], v[98:99]
	v_mov_b32_e32 v100, v60
	v_mov_b32_e32 v101, v74
	v_pk_add_f32 v[62:63], v[116:117], v[46:47] op_sel_hi:[1,0] neg_lo:[0,1] neg_hi:[0,1]
	v_pk_fma_f32 v[98:99], v[100:101], v[100:101], v[98:99]
	v_mov_b32_e32 v100, v61
	v_mov_b32_e32 v101, v75
	v_pk_fma_f32 v[98:99], v[100:101], v[100:101], v[98:99]
	v_mov_b32_e32 v100, v62
	v_mov_b32_e32 v101, v76
	v_pk_add_f32 v[8:9], v[10:11], v[46:47] op_sel_hi:[1,0] neg_lo:[0,1] neg_hi:[0,1]
	v_pk_fma_f32 v[98:99], v[100:101], v[100:101], v[98:99]
	v_mov_b32_e32 v100, v63
	v_mov_b32_e32 v101, v77
	v_pk_fma_f32 v[98:99], v[100:101], v[100:101], v[98:99]
	v_mov_b32_e32 v100, v8
	v_mov_b32_e32 v101, v70
	v_pk_add_f32 v[38:39], v[124:125], v[46:47] op_sel_hi:[1,0] neg_lo:[0,1] neg_hi:[0,1]
	v_pk_fma_f32 v[98:99], v[100:101], v[100:101], v[98:99]
	v_mov_b32_e32 v100, v9
	v_mov_b32_e32 v101, v71
	v_pk_add_f32 v[10:11], v[122:123], v[46:47] op_sel_hi:[1,0] neg_lo:[0,1] neg_hi:[0,1]
	v_pk_fma_f32 v[98:99], v[100:101], v[100:101], v[98:99]
	v_mov_b32_e32 v100, v38
	v_mov_b32_e32 v101, v72
	v_pk_mul_f32 v[102:103], v[10:11], v[10:11]
	v_pk_fma_f32 v[98:99], v[100:101], v[100:101], v[98:99]
	v_mov_b32_e32 v100, v39
	v_mov_b32_e32 v101, v73
	v_pk_fma_f32 v[98:99], v[100:101], v[100:101], v[98:99]
	v_mov_b32_e32 v100, v102
	v_mov_b32_e32 v101, v142
	v_pk_add_f32 v[46:47], v[82:83], v[46:47] op_sel_hi:[1,0] neg_lo:[0,1] neg_hi:[0,1]
	v_pk_mul_f32 v[144:145], v[68:69], v[68:69]
	v_pk_add_f32 v[98:99], v[100:101], v[98:99]
	v_pk_mul_f32 v[82:83], v[46:47], v[46:47]
	v_mov_b32_e32 v142, v103
	v_pk_add_f32 v[98:99], v[142:143], v[98:99]
	v_mov_b32_e32 v100, v82
	v_mov_b32_e32 v101, v144
	v_pk_add_f32 v[98:99], v[100:101], v[98:99]
	v_mov_b32_e32 v144, v83
	v_pk_add_f32 v[82:83], v[144:145], v[98:99]
	ds_bpermute_b32 v99, v33, v83
	ds_bpermute_b32 v98, v33, v82
	s_waitcnt lgkmcnt(0)
; __device__ void ln_final_phase(const h16* z0, const float* g0, const float* b0, float* out0) {
;     ...
;             const float rstd = rsqrtf(q * (1.0f / DM) + LN_EPS);
; #pragma unroll
;             for (int i = 0; i < 4; ++i) { const int col = 8 * (lane + 64 * i);
;                 const f32x4 g0v = ldg4(g + col), g1v = ldg4(g + col + 4), b0v = ldg4(b + col), b1v = ldg4(b + col + 4);
;                 f32x4 y0, y1;
; #pragma unroll
;                 for (int j = 0; j < 4; ++j) { y0[j] = ((float)hv[r][i][j] - mean) * rstd * g0v[j] + b0v[j]; y1[j] = ((float)hv[r][i][4 + j] - mean) * rstd * g1v[j] + b1v[j]; }
;                 stg4(out + (size_t)row * DM + col, y0); stg4(out + (size_t)row * DM + col + 4, y1); }
	v_pk_add_f32 v[82:83], v[82:83], v[98:99]
	ds_bpermute_b32 v99, v84, v83
	ds_bpermute_b32 v98, v84, v82
	s_waitcnt lgkmcnt(0)
	v_pk_add_f32 v[82:83], v[82:83], v[98:99]
	ds_bpermute_b32 v99, v85, v83
	ds_bpermute_b32 v98, v85, v82
	s_waitcnt lgkmcnt(0)
	v_pk_add_f32 v[82:83], v[82:83], v[98:99]
	ds_bpermute_b32 v99, v86, v83
	ds_bpermute_b32 v98, v86, v82
	s_waitcnt lgkmcnt(0)
	v_pk_add_f32 v[82:83], v[82:83], v[98:99]
	ds_bpermute_b32 v99, v87, v83
	ds_bpermute_b32 v98, v87, v82
	s_waitcnt lgkmcnt(0)
	v_pk_add_f32 v[82:83], v[82:83], v[98:99]
	ds_bpermute_b32 v99, v88, v83
	ds_bpermute_b32 v98, v88, v82
	s_waitcnt lgkmcnt(0)
	v_pk_add_f32 v[82:83], v[82:83], v[98:99]
	s_nop 0
	v_pk_fma_f32 v[82:83], v[82:83], s[2:3], v[32:33] op_sel_hi:[1,0,0]
	v_lshl_add_u64 v[98:99], v[36:37], 0, v[12:13]
	v_mul_f32_e32 v89, 0x4b800000, v83
	v_cmp_gt_f32_e32 vcc, s3, v83
	s_nop 1
	v_cndmask_b32_e32 v83, v83, v89, vcc
	v_rsq_f32_e32 v83, v83
	s_nop 0
	v_mul_f32_e32 v89, 0x45800000, v83
	v_cndmask_b32_e32 v100, v83, v89, vcc
	v_pk_mul_f32 v[102:103], v[126:127], v[100:101] op_sel_hi:[1,0]
	v_pk_mul_f32 v[104:105], v[128:129], v[100:101] op_sel_hi:[1,0]
	v_pk_fma_f32 v[4:5], v[4:5], v[102:103], v[94:95]
	v_pk_fma_f32 v[6:7], v[6:7], v[104:105], v[96:97]
	v_pk_mul_f32 v[94:95], v[130:131], v[100:101] op_sel_hi:[1,0]
	v_pk_mul_f32 v[96:97], v[132:133], v[100:101] op_sel_hi:[1,0]
	v_pk_fma_f32 v[0:1], v[0:1], v[94:95], v[90:91]
	v_pk_fma_f32 v[2:3], v[2:3], v[96:97], v[92:93]
	global_store_dwordx4 v[98:99], v[4:7], off
	global_store_dwordx4 v[98:99], v[0:3], off offset:16
	s_nop 1
	v_mov_b32_e32 v0, v190
	v_mov_b32_e32 v1, v191
	v_mov_b32_e32 v2, v192
	v_mov_b32_e32 v3, v193
	s_nop 0
	v_mov_b32_e32 v4, v158
	v_mov_b32_e32 v5, v159
	v_mov_b32_e32 v6, v160
	v_mov_b32_e32 v7, v161
	v_mov_b32_e32 v90, v162
	v_mov_b32_e32 v91, v163
	v_mov_b32_e32 v92, v164
	v_mov_b32_e32 v93, v165
	v_mov_b32_e32 v94, v194
	v_mov_b32_e32 v95, v195
	v_mov_b32_e32 v96, v196
	v_mov_b32_e32 v97, v197
	v_pk_mul_f32 v[102:103], v[136:137], v[100:101] op_sel_hi:[1,0]
	v_pk_mul_f32 v[104:105], v[134:135], v[100:101] op_sel_hi:[1,0]
	v_pk_mul_f32 v[80:81], v[80:81], v[100:101] op_sel_hi:[1,0]
	v_pk_mul_f32 v[78:79], v[78:79], v[100:101] op_sel_hi:[1,0]
	v_pk_mul_f32 v[76:77], v[76:77], v[100:101] op_sel_hi:[1,0]
	v_pk_mul_f32 v[74:75], v[74:75], v[100:101] op_sel_hi:[1,0]
	v_pk_mul_f32 v[72:73], v[72:73], v[100:101] op_sel_hi:[1,0]
	v_pk_mul_f32 v[70:71], v[70:71], v[100:101] op_sel_hi:[1,0]
	v_pk_mul_f32 v[68:69], v[68:69], v[100:101] op_sel_hi:[1,0]
	v_pk_mul_f32 v[66:67], v[66:67], v[100:101] op_sel_hi:[1,0]
	v_cmp_gt_f32_e32 vcc, s3, v82
	v_pk_fma_f32 v[0:1], v[4:5], v[104:105], v[0:1]
	v_pk_fma_f32 v[2:3], v[6:7], v[102:103], v[2:3]
	v_pk_mul_f32 v[6:7], v[140:141], v[100:101] op_sel_hi:[1,0]
	v_pk_mul_f32 v[4:5], v[138:139], v[100:101] op_sel_hi:[1,0]
	v_pk_fma_f32 v[6:7], v[92:93], v[6:7], v[96:97]
	v_pk_fma_f32 v[4:5], v[90:91], v[4:5], v[94:95]
	global_store_dwordx4 v[98:99], v[0:3], off offset:2048
	global_store_dwordx4 v[98:99], v[4:7], off offset:2064
	s_nop 1
	v_mov_b32_e32 v0, v198
	v_mov_b32_e32 v1, v199
	v_mov_b32_e32 v2, v200
	v_mov_b32_e32 v3, v201
	s_nop 0
	v_mov_b32_e32 v4, v166
	v_mov_b32_e32 v5, v167
	v_mov_b32_e32 v6, v168
	v_mov_b32_e32 v7, v169
	v_mov_b32_e32 v90, v170
	v_mov_b32_e32 v91, v171
	v_mov_b32_e32 v92, v172
	v_mov_b32_e32 v93, v173
	v_mov_b32_e32 v94, v202
	v_mov_b32_e32 v95, v203
	v_mov_b32_e32 v96, v204
	v_mov_b32_e32 v97, v205
	v_lshl_add_u64 v[98:99], v[36:37], 0, v[28:29]
	v_lshl_add_u64 v[36:37], v[36:37], 0, v[30:31]
	v_pk_fma_f32 v[0:1], v[4:5], v[78:79], v[0:1]
	v_pk_fma_f32 v[2:3], v[6:7], v[80:81], v[2:3]
	v_pk_fma_f32 v[4:5], v[90:91], v[74:75], v[94:95]
	v_pk_fma_f32 v[6:7], v[92:93], v[76:77], v[96:97]
	global_store_dwordx4 v[98:99], v[0:3], off
	global_store_dwordx4 v[98:99], v[4:7], off offset:16
	s_nop 1
	v_mov_b32_e32 v0, v206
	v_mov_b32_e32 v1, v207
	v_mov_b32_e32 v2, v208
	v_mov_b32_e32 v3, v209
	s_nop 0
	v_mov_b32_e32 v4, v174
	v_mov_b32_e32 v5, v175
	v_mov_b32_e32 v6, v176
	v_mov_b32_e32 v7, v177
	v_mov_b32_e32 v74, v178
	v_mov_b32_e32 v75, v179
	v_mov_b32_e32 v76, v180
	v_mov_b32_e32 v77, v181
	v_mov_b32_e32 v78, v210
	v_mov_b32_e32 v79, v211
	v_mov_b32_e32 v80, v212
	v_mov_b32_e32 v81, v213
	v_pk_fma_f32 v[0:1], v[4:5], v[70:71], v[0:1]
	v_pk_fma_f32 v[2:3], v[6:7], v[72:73], v[2:3]
	v_pk_fma_f32 v[4:5], v[74:75], v[66:67], v[78:79]
; __device__ void ln_final_phase(const h16* z0, const float* g0, const float* b0, float* out0) {
;     ...
;             const float rstd = rsqrtf(q * (1.0f / DM) + LN_EPS);
; #pragma unroll
;             for (int i = 0; i < 4; ++i) { const int col = 8 * (lane + 64 * i);
;                 const f32x4 g0v = ldg4(g + col), g1v = ldg4(g + col + 4), b0v = ldg4(b + col), b1v = ldg4(b + col + 4);
;                 f32x4 y0, y1;
; #pragma unroll
;                 for (int j = 0; j < 4; ++j) { y0[j] = ((float)hv[r][i][j] - mean) * rstd * g0v[j] + b0v[j]; y1[j] = ((float)hv[r][i][4 + j] - mean) * rstd * g1v[j] + b1v[j]; }
;                 stg4(out + (size_t)row * DM + col, y0); stg4(out + (size_t)row * DM + col + 4, y1); }
;         }
;     }
	v_pk_fma_f32 v[6:7], v[76:77], v[68:69], v[80:81]
	global_store_dwordx4 v[36:37], v[0:3], off
	global_store_dwordx4 v[36:37], v[4:7], off offset:16
	s_nop 1
	v_mov_b32_e32 v0, v182
	v_mov_b32_e32 v1, v183
	v_mov_b32_e32 v2, v184
	v_mov_b32_e32 v3, v185
	s_nop 0
	v_mov_b32_e32 v4, v150
	v_mov_b32_e32 v5, v151
	v_mov_b32_e32 v6, v152
	v_mov_b32_e32 v7, v153
	v_mov_b32_e32 v66, v154
	v_mov_b32_e32 v67, v155
	v_mov_b32_e32 v68, v156
	v_mov_b32_e32 v69, v157
	v_mov_b32_e32 v70, v186
	v_mov_b32_e32 v71, v187
	v_mov_b32_e32 v72, v188
	v_mov_b32_e32 v73, v189
	v_mul_f32_e32 v36, 0x4b800000, v82
	v_cndmask_b32_e32 v36, v82, v36, vcc
	v_rsq_f32_e32 v76, v36
	v_lshlrev_b64 v[36:37], 13, v[34:35]
	v_lshl_add_u64 v[74:75], s[50:51], 0, v[36:37]
	v_lshl_add_u64 v[36:37], v[74:75], 0, v[12:13]
	v_mul_f32_e32 v35, 0x45800000, v76
	v_cndmask_b32_e32 v76, v76, v35, vcc
	v_pk_mul_f32 v[56:57], v[56:57], v[76:77] op_sel_hi:[1,0]
	v_pk_mul_f32 v[52:53], v[52:53], v[76:77] op_sel_hi:[1,0]
	v_pk_mul_f32 v[48:49], v[48:49], v[76:77] op_sel_hi:[1,0]
	v_pk_mul_f32 v[42:43], v[42:43], v[76:77] op_sel_hi:[1,0]
	v_pk_mul_f32 v[50:51], v[50:51], v[76:77] op_sel_hi:[1,0]
	v_pk_mul_f32 v[44:45], v[44:45], v[76:77] op_sel_hi:[1,0]
	v_pk_mul_f32 v[40:41], v[40:41], v[76:77] op_sel_hi:[1,0]
	v_pk_mul_f32 v[38:39], v[38:39], v[76:77] op_sel_hi:[1,0]
	v_pk_mul_f32 v[8:9], v[8:9], v[76:77] op_sel_hi:[1,0]
	v_pk_mul_f32 v[10:11], v[10:11], v[76:77] op_sel_hi:[1,0]
	v_pk_fma_f32 v[0:1], v[4:5], v[52:53], v[0:1]
	v_pk_fma_f32 v[2:3], v[6:7], v[56:57], v[2:3]
	v_pk_fma_f32 v[4:5], v[66:67], v[42:43], v[70:71]
	v_pk_fma_f32 v[6:7], v[68:69], v[48:49], v[72:73]
	global_store_dwordx4 v[36:37], v[0:3], off
	global_store_dwordx4 v[36:37], v[4:7], off offset:16
	s_nop 1
	v_mov_b32_e32 v0, v190
	v_mov_b32_e32 v1, v191
	v_mov_b32_e32 v2, v192
	v_mov_b32_e32 v3, v193
	s_nop 0
	v_mov_b32_e32 v4, v158
	v_mov_b32_e32 v5, v159
	v_mov_b32_e32 v6, v160
	v_mov_b32_e32 v7, v161
	v_mov_b32_e32 v66, v162
	v_mov_b32_e32 v67, v163
	v_mov_b32_e32 v68, v164
	v_mov_b32_e32 v69, v165
	v_mov_b32_e32 v70, v194
	v_mov_b32_e32 v71, v195
	v_mov_b32_e32 v72, v196
	v_mov_b32_e32 v73, v197
	v_pk_mul_f32 v[42:43], v[58:59], v[76:77] op_sel_hi:[1,0]
	v_pk_mul_f32 v[48:49], v[54:55], v[76:77] op_sel_hi:[1,0]
	v_pk_mul_f32 v[52:53], v[64:65], v[76:77] op_sel_hi:[1,0]
	v_pk_mul_f32 v[54:55], v[62:63], v[76:77] op_sel_hi:[1,0]
	v_pk_mul_f32 v[56:57], v[60:61], v[76:77] op_sel_hi:[1,0]
	v_pk_fma_f32 v[0:1], v[4:5], v[48:49], v[0:1]
	v_pk_fma_f32 v[2:3], v[6:7], v[42:43], v[2:3]
	v_pk_fma_f32 v[4:5], v[66:67], v[44:45], v[70:71]
	v_pk_fma_f32 v[6:7], v[68:69], v[50:51], v[72:73]
	global_store_dwordx4 v[36:37], v[0:3], off offset:2048
	global_store_dwordx4 v[36:37], v[4:7], off offset:2064
	s_nop 1
	v_mov_b32_e32 v0, v198
	v_mov_b32_e32 v1, v199
	v_mov_b32_e32 v2, v200
	v_mov_b32_e32 v3, v201
	s_nop 0
	v_mov_b32_e32 v4, v166
	v_mov_b32_e32 v5, v167
	v_mov_b32_e32 v6, v168
	v_mov_b32_e32 v7, v169
	v_mov_b32_e32 v42, v170
	v_mov_b32_e32 v43, v171
	v_mov_b32_e32 v44, v172
	v_mov_b32_e32 v45, v173
	v_mov_b32_e32 v48, v202
	v_mov_b32_e32 v49, v203
	v_mov_b32_e32 v50, v204
	v_mov_b32_e32 v51, v205
	v_lshl_add_u64 v[36:37], v[74:75], 0, v[28:29]
	v_pk_fma_f32 v[0:1], v[4:5], v[40:41], v[0:1]
	v_pk_fma_f32 v[2:3], v[6:7], v[52:53], v[2:3]
	v_pk_fma_f32 v[4:5], v[42:43], v[56:57], v[48:49]
	v_pk_fma_f32 v[6:7], v[44:45], v[54:55], v[50:51]
	global_store_dwordx4 v[36:37], v[0:3], off
	global_store_dwordx4 v[36:37], v[4:7], off offset:16
	s_nop 1
	v_mov_b32_e32 v0, v206
	v_mov_b32_e32 v1, v207
	v_mov_b32_e32 v2, v208
	v_mov_b32_e32 v3, v209
	s_nop 0
	v_mov_b32_e32 v4, v174
	v_mov_b32_e32 v5, v175
	v_mov_b32_e32 v6, v176
	v_mov_b32_e32 v7, v177
	v_mov_b32_e32 v40, v178
	v_mov_b32_e32 v41, v179
	v_mov_b32_e32 v42, v180
	v_mov_b32_e32 v43, v181
	v_mov_b32_e32 v48, v210
	v_mov_b32_e32 v49, v211
	v_mov_b32_e32 v50, v212
	v_mov_b32_e32 v51, v213
	v_add_u32_e32 v36, s6, v34
	v_cmp_lt_i32_e32 vcc, s4, v36
	s_or_b64 s[0:1], vcc, s[0:1]
	v_lshl_add_u64 v[34:35], v[74:75], 0, v[30:31]
	v_pk_mul_f32 v[44:45], v[46:47], v[76:77] op_sel_hi:[1,0]
	v_pk_fma_f32 v[0:1], v[4:5], v[8:9], v[0:1]
	v_pk_fma_f32 v[2:3], v[6:7], v[38:39], v[2:3]
	v_pk_fma_f32 v[4:5], v[40:41], v[10:11], v[48:49]
	v_pk_fma_f32 v[6:7], v[42:43], v[44:45], v[50:51]
	global_store_dwordx4 v[34:35], v[0:3], off
	global_store_dwordx4 v[34:35], v[4:7], off offset:16
	s_andn2_b64 exec, exec, s[0:1]
	s_cbranch_execnz .LBB0_807
